# PEER U loop: index waits lgkmcnt(1)/(0) -> (3)/(2) with an exactly-two-op LDS tail on every path, so the just-issued LDS accumulates are no longer waited for before the next gathers
# baseline (speedup 1.0000x reference)
.LBB0_1375:
	v_max_u32_dpp v31, v72, v72 row_ror:1 row_mask:0xf bank_mask:0xf bound_ctrl:1
	v_max_u32_dpp v30, v76, v76 row_ror:1 row_mask:0xf bank_mask:0xf bound_ctrl:1
	v_max_u32_dpp v32, v80, v80 row_ror:1 row_mask:0xf bank_mask:0xf bound_ctrl:1
	v_max_u32_dpp v31, v31, v31 row_ror:2 row_mask:0xf bank_mask:0xf bound_ctrl:1
	v_max_u32_dpp v33, v84, v84 row_ror:1 row_mask:0xf bank_mask:0xf bound_ctrl:1
	v_max_u32_dpp v30, v30, v30 row_ror:2 row_mask:0xf bank_mask:0xf bound_ctrl:1
	v_max_u32_dpp v32, v32, v32 row_ror:2 row_mask:0xf bank_mask:0xf bound_ctrl:1
	v_max_u32_dpp v31, v31, v31 row_ror:4 row_mask:0xf bank_mask:0xf bound_ctrl:1
	v_max_u32_dpp v33, v33, v33 row_ror:2 row_mask:0xf bank_mask:0xf bound_ctrl:1
	v_max_u32_dpp v30, v30, v30 row_ror:4 row_mask:0xf bank_mask:0xf bound_ctrl:1
	v_max_u32_dpp v32, v32, v32 row_ror:4 row_mask:0xf bank_mask:0xf bound_ctrl:1
	v_max_u32_dpp v31, v31, v31 row_ror:8 row_mask:0xf bank_mask:0xf bound_ctrl:1
	v_max_u32_dpp v33, v33, v33 row_ror:4 row_mask:0xf bank_mask:0xf bound_ctrl:1
	v_max_u32_dpp v30, v30, v30 row_ror:8 row_mask:0xf bank_mask:0xf bound_ctrl:1
	v_max_u32_dpp v32, v32, v32 row_ror:8 row_mask:0xf bank_mask:0xf bound_ctrl:1
	v_max_u32_dpp v33, v33, v33 row_ror:8 row_mask:0xf bank_mask:0xf bound_ctrl:1
	v_cmp_eq_u32_e64 s[84:85], v72, v31
	v_cmp_eq_u32_e64 s[86:87], v76, v30
	v_cmp_eq_u32_e64 s[88:89], v80, v32
	v_cmp_eq_u32_e64 s[90:91], v84, v33
	s_mov_b64 exec, s[84:85]
	v_pk_mov_b32 v[72:73], v[72:73], v[74:75] op_sel:[1,0] op_sel_hi:[1,0]
	v_pk_mov_b32 v[74:75], v[74:75], v[70:71] op_sel:[1,0] op_sel_hi:[1,0]
	s_mov_b64 exec, s[86:87]
	v_pk_mov_b32 v[76:77], v[76:77], v[78:79] op_sel:[1,0] op_sel_hi:[1,0]
	v_pk_mov_b32 v[78:79], v[78:79], v[70:71] op_sel:[1,0] op_sel_hi:[1,0]
	s_mov_b64 exec, s[88:89]
	v_pk_mov_b32 v[80:81], v[80:81], v[82:83] op_sel:[1,0] op_sel_hi:[1,0]
	v_pk_mov_b32 v[82:83], v[82:83], v[70:71] op_sel:[1,0] op_sel_hi:[1,0]
	s_mov_b64 exec, s[90:91]
	v_pk_mov_b32 v[84:85], v[84:85], v[86:87] op_sel:[1,0] op_sel_hi:[1,0]
	v_pk_mov_b32 v[86:87], v[86:87], v[70:71] op_sel:[1,0] op_sel_hi:[1,0]
	s_lshl_b64 exec, s[78:79], s40
	s_add_i32 s40, s40, 1
	v_pk_mov_b32 v[4:5], v[32:33], v[32:33] op_sel:[1,0] op_sel_hi:[1,0]
	v_pk_mov_b32 v[6:7], v[30:31], v[30:31] op_sel:[1,0] op_sel_hi:[1,0]
	s_mov_b64 exec, -1
	s_cmp_lg_u32 s40, 8
	s_cbranch_scc1 .LBB0_1375
	v_max_u32_dpp v31, v72, v72 row_ror:1 row_mask:0xf bank_mask:0xf bound_ctrl:1
	v_max_u32_dpp v30, v76, v76 row_ror:1 row_mask:0xf bank_mask:0xf bound_ctrl:1
	v_max_u32_dpp v32, v80, v80 row_ror:1 row_mask:0xf bank_mask:0xf bound_ctrl:1
	v_max_u32_dpp v31, v31, v31 row_ror:2 row_mask:0xf bank_mask:0xf bound_ctrl:1
	v_max_u32_dpp v33, v84, v84 row_ror:1 row_mask:0xf bank_mask:0xf bound_ctrl:1
	v_max_u32_dpp v30, v30, v30 row_ror:2 row_mask:0xf bank_mask:0xf bound_ctrl:1
	v_max_u32_dpp v32, v32, v32 row_ror:2 row_mask:0xf bank_mask:0xf bound_ctrl:1
	v_max_u32_dpp v31, v31, v31 row_ror:4 row_mask:0xf bank_mask:0xf bound_ctrl:1
	v_max_u32_dpp v33, v33, v33 row_ror:2 row_mask:0xf bank_mask:0xf bound_ctrl:1
	v_max_u32_dpp v30, v30, v30 row_ror:4 row_mask:0xf bank_mask:0xf bound_ctrl:1
	v_max_u32_dpp v32, v32, v32 row_ror:4 row_mask:0xf bank_mask:0xf bound_ctrl:1
	v_max_u32_dpp v31, v31, v31 row_ror:8 row_mask:0xf bank_mask:0xf bound_ctrl:1
	v_max_u32_dpp v33, v33, v33 row_ror:4 row_mask:0xf bank_mask:0xf bound_ctrl:1
	v_max_u32_dpp v30, v30, v30 row_ror:8 row_mask:0xf bank_mask:0xf bound_ctrl:1
	v_max_u32_dpp v32, v32, v32 row_ror:8 row_mask:0xf bank_mask:0xf bound_ctrl:1
	v_max_u32_dpp v33, v33, v33 row_ror:8 row_mask:0xf bank_mask:0xf bound_ctrl:1
	v_cmp_eq_u32_e64 s[84:85], v72, v31
	v_cmp_eq_u32_e64 s[86:87], v76, v30
	v_cmp_eq_u32_e64 s[88:89], v80, v32
	v_cmp_eq_u32_e64 s[90:91], v84, v33
	s_mov_b64 exec, s[84:85]
	v_pk_mov_b32 v[72:73], v[72:73], v[74:75] op_sel:[1,0] op_sel_hi:[1,0]
	v_pk_mov_b32 v[74:75], v[74:75], v[70:71] op_sel:[1,0] op_sel_hi:[1,0]
	s_mov_b64 exec, s[86:87]
	v_pk_mov_b32 v[76:77], v[76:77], v[78:79] op_sel:[1,0] op_sel_hi:[1,0]
	v_pk_mov_b32 v[78:79], v[78:79], v[70:71] op_sel:[1,0] op_sel_hi:[1,0]
	s_mov_b64 exec, s[88:89]
	v_pk_mov_b32 v[80:81], v[80:81], v[82:83] op_sel:[1,0] op_sel_hi:[1,0]
	v_pk_mov_b32 v[82:83], v[82:83], v[70:71] op_sel:[1,0] op_sel_hi:[1,0]
	s_mov_b64 exec, s[90:91]
	v_pk_mov_b32 v[84:85], v[84:85], v[86:87] op_sel:[1,0] op_sel_hi:[1,0]
	v_pk_mov_b32 v[86:87], v[86:87], v[70:71] op_sel:[1,0] op_sel_hi:[1,0]
	s_lshl_b64 exec, s[78:79], s40
	s_add_i32 s40, s40, 1
	v_pk_mov_b32 v[4:5], v[32:33], v[32:33] op_sel:[1,0] op_sel_hi:[1,0]
	v_pk_mov_b32 v[6:7], v[30:31], v[30:31] op_sel:[1,0] op_sel_hi:[1,0]
	s_mov_b64 exec, -1
	v_max_u32_dpp v31, v72, v72 row_ror:1 row_mask:0xf bank_mask:0xf bound_ctrl:1
	v_max_u32_dpp v30, v76, v76 row_ror:1 row_mask:0xf bank_mask:0xf bound_ctrl:1
	v_max_u32_dpp v32, v80, v80 row_ror:1 row_mask:0xf bank_mask:0xf bound_ctrl:1
	v_max_u32_dpp v31, v31, v31 row_ror:2 row_mask:0xf bank_mask:0xf bound_ctrl:1
	v_max_u32_dpp v33, v84, v84 row_ror:1 row_mask:0xf bank_mask:0xf bound_ctrl:1
	v_max_u32_dpp v30, v30, v30 row_ror:2 row_mask:0xf bank_mask:0xf bound_ctrl:1
	v_max_u32_dpp v32, v32, v32 row_ror:2 row_mask:0xf bank_mask:0xf bound_ctrl:1
	v_max_u32_dpp v31, v31, v31 row_ror:4 row_mask:0xf bank_mask:0xf bound_ctrl:1
	v_max_u32_dpp v33, v33, v33 row_ror:2 row_mask:0xf bank_mask:0xf bound_ctrl:1
	v_max_u32_dpp v30, v30, v30 row_ror:4 row_mask:0xf bank_mask:0xf bound_ctrl:1
	v_max_u32_dpp v32, v32, v32 row_ror:4 row_mask:0xf bank_mask:0xf bound_ctrl:1
	v_max_u32_dpp v31, v31, v31 row_ror:8 row_mask:0xf bank_mask:0xf bound_ctrl:1
	v_max_u32_dpp v33, v33, v33 row_ror:4 row_mask:0xf bank_mask:0xf bound_ctrl:1
	v_max_u32_dpp v30, v30, v30 row_ror:8 row_mask:0xf bank_mask:0xf bound_ctrl:1
	v_max_u32_dpp v32, v32, v32 row_ror:8 row_mask:0xf bank_mask:0xf bound_ctrl:1
	v_max_u32_dpp v33, v33, v33 row_ror:8 row_mask:0xf bank_mask:0xf bound_ctrl:1
	v_cmp_eq_u32_e64 s[84:85], v72, v31
	v_cmp_eq_u32_e64 s[86:87], v76, v30
	v_cmp_eq_u32_e64 s[88:89], v80, v32
	v_cmp_eq_u32_e64 s[90:91], v84, v33
	s_mov_b64 exec, s[84:85]
	v_pk_mov_b32 v[72:73], v[72:73], v[74:75] op_sel:[1,0] op_sel_hi:[1,0]
	v_pk_mov_b32 v[74:75], v[74:75], v[70:71] op_sel:[1,0] op_sel_hi:[1,0]
	s_mov_b64 exec, s[86:87]
	v_pk_mov_b32 v[76:77], v[76:77], v[78:79] op_sel:[1,0] op_sel_hi:[1,0]
	v_pk_mov_b32 v[78:79], v[78:79], v[70:71] op_sel:[1,0] op_sel_hi:[1,0]
	s_mov_b64 exec, s[88:89]
	v_pk_mov_b32 v[80:81], v[80:81], v[82:83] op_sel:[1,0] op_sel_hi:[1,0]
	v_pk_mov_b32 v[82:83], v[82:83], v[70:71] op_sel:[1,0] op_sel_hi:[1,0]
	s_mov_b64 exec, s[90:91]
	v_pk_mov_b32 v[84:85], v[84:85], v[86:87] op_sel:[1,0] op_sel_hi:[1,0]
	v_pk_mov_b32 v[86:87], v[86:87], v[70:71] op_sel:[1,0] op_sel_hi:[1,0]
	s_lshl_b64 exec, s[78:79], s40
	s_add_i32 s40, s40, 1
	v_pk_mov_b32 v[4:5], v[32:33], v[32:33] op_sel:[1,0] op_sel_hi:[1,0]
	v_pk_mov_b32 v[6:7], v[30:31], v[30:31] op_sel:[1,0] op_sel_hi:[1,0]
	s_mov_b64 exec, -1
	v_max_u32_dpp v31, v72, v72 row_ror:1 row_mask:0xf bank_mask:0xf bound_ctrl:1
	v_max_u32_dpp v30, v76, v76 row_ror:1 row_mask:0xf bank_mask:0xf bound_ctrl:1
	v_max_u32_dpp v32, v80, v80 row_ror:1 row_mask:0xf bank_mask:0xf bound_ctrl:1
	v_max_u32_dpp v31, v31, v31 row_ror:2 row_mask:0xf bank_mask:0xf bound_ctrl:1
	v_max_u32_dpp v33, v84, v84 row_ror:1 row_mask:0xf bank_mask:0xf bound_ctrl:1
	v_max_u32_dpp v30, v30, v30 row_ror:2 row_mask:0xf bank_mask:0xf bound_ctrl:1
	v_max_u32_dpp v32, v32, v32 row_ror:2 row_mask:0xf bank_mask:0xf bound_ctrl:1
	v_max_u32_dpp v31, v31, v31 row_ror:4 row_mask:0xf bank_mask:0xf bound_ctrl:1
	v_max_u32_dpp v33, v33, v33 row_ror:2 row_mask:0xf bank_mask:0xf bound_ctrl:1
	v_max_u32_dpp v30, v30, v30 row_ror:4 row_mask:0xf bank_mask:0xf bound_ctrl:1
	v_max_u32_dpp v32, v32, v32 row_ror:4 row_mask:0xf bank_mask:0xf bound_ctrl:1
	v_max_u32_dpp v31, v31, v31 row_ror:8 row_mask:0xf bank_mask:0xf bound_ctrl:1
	v_max_u32_dpp v33, v33, v33 row_ror:4 row_mask:0xf bank_mask:0xf bound_ctrl:1
	v_max_u32_dpp v30, v30, v30 row_ror:8 row_mask:0xf bank_mask:0xf bound_ctrl:1
	v_max_u32_dpp v32, v32, v32 row_ror:8 row_mask:0xf bank_mask:0xf bound_ctrl:1
	v_max_u32_dpp v33, v33, v33 row_ror:8 row_mask:0xf bank_mask:0xf bound_ctrl:1
	v_cmp_eq_u32_e64 s[84:85], v72, v31
	v_cmp_eq_u32_e64 s[86:87], v76, v30
	v_cmp_eq_u32_e64 s[88:89], v80, v32
	v_cmp_eq_u32_e64 s[90:91], v84, v33
	s_mov_b64 exec, s[84:85]
	v_pk_mov_b32 v[72:73], v[72:73], v[74:75] op_sel:[1,0] op_sel_hi:[1,0]
	v_pk_mov_b32 v[74:75], v[74:75], v[70:71] op_sel:[1,0] op_sel_hi:[1,0]
	s_mov_b64 exec, s[86:87]
	v_pk_mov_b32 v[76:77], v[76:77], v[78:79] op_sel:[1,0] op_sel_hi:[1,0]
	v_pk_mov_b32 v[78:79], v[78:79], v[70:71] op_sel:[1,0] op_sel_hi:[1,0]
	s_mov_b64 exec, s[88:89]
	v_pk_mov_b32 v[80:81], v[80:81], v[82:83] op_sel:[1,0] op_sel_hi:[1,0]
	v_pk_mov_b32 v[82:83], v[82:83], v[70:71] op_sel:[1,0] op_sel_hi:[1,0]
	s_mov_b64 exec, s[90:91]
	v_pk_mov_b32 v[84:85], v[84:85], v[86:87] op_sel:[1,0] op_sel_hi:[1,0]
	v_pk_mov_b32 v[86:87], v[86:87], v[70:71] op_sel:[1,0] op_sel_hi:[1,0]
	s_lshl_b64 exec, s[78:79], s40
	s_add_i32 s40, s40, 1
	v_pk_mov_b32 v[4:5], v[32:33], v[32:33] op_sel:[1,0] op_sel_hi:[1,0]
	v_pk_mov_b32 v[6:7], v[30:31], v[30:31] op_sel:[1,0] op_sel_hi:[1,0]
	s_mov_b64 exec, -1
	v_max_u32_dpp v31, v72, v72 row_ror:1 row_mask:0xf bank_mask:0xf bound_ctrl:1
	v_max_u32_dpp v30, v76, v76 row_ror:1 row_mask:0xf bank_mask:0xf bound_ctrl:1
	v_max_u32_dpp v32, v80, v80 row_ror:1 row_mask:0xf bank_mask:0xf bound_ctrl:1
	v_max_u32_dpp v31, v31, v31 row_ror:2 row_mask:0xf bank_mask:0xf bound_ctrl:1
	v_max_u32_dpp v33, v84, v84 row_ror:1 row_mask:0xf bank_mask:0xf bound_ctrl:1
	v_max_u32_dpp v30, v30, v30 row_ror:2 row_mask:0xf bank_mask:0xf bound_ctrl:1
	v_max_u32_dpp v32, v32, v32 row_ror:2 row_mask:0xf bank_mask:0xf bound_ctrl:1
	v_max_u32_dpp v31, v31, v31 row_ror:4 row_mask:0xf bank_mask:0xf bound_ctrl:1
	v_max_u32_dpp v33, v33, v33 row_ror:2 row_mask:0xf bank_mask:0xf bound_ctrl:1
	v_max_u32_dpp v30, v30, v30 row_ror:4 row_mask:0xf bank_mask:0xf bound_ctrl:1
	v_max_u32_dpp v32, v32, v32 row_ror:4 row_mask:0xf bank_mask:0xf bound_ctrl:1
	v_max_u32_dpp v31, v31, v31 row_ror:8 row_mask:0xf bank_mask:0xf bound_ctrl:1
	v_max_u32_dpp v33, v33, v33 row_ror:4 row_mask:0xf bank_mask:0xf bound_ctrl:1
	v_max_u32_dpp v30, v30, v30 row_ror:8 row_mask:0xf bank_mask:0xf bound_ctrl:1
	v_max_u32_dpp v32, v32, v32 row_ror:8 row_mask:0xf bank_mask:0xf bound_ctrl:1
	v_max_u32_dpp v33, v33, v33 row_ror:8 row_mask:0xf bank_mask:0xf bound_ctrl:1
	v_cmp_eq_u32_e64 s[84:85], v72, v31
	v_cmp_eq_u32_e64 s[86:87], v76, v30
	v_cmp_eq_u32_e64 s[88:89], v80, v32
	v_cmp_eq_u32_e64 s[90:91], v84, v33
	s_mov_b64 exec, s[84:85]
	v_pk_mov_b32 v[72:73], v[72:73], v[74:75] op_sel:[1,0] op_sel_hi:[1,0]
	v_pk_mov_b32 v[74:75], v[74:75], v[70:71] op_sel:[1,0] op_sel_hi:[1,0]
	s_mov_b64 exec, s[86:87]
	v_pk_mov_b32 v[76:77], v[76:77], v[78:79] op_sel:[1,0] op_sel_hi:[1,0]
	v_pk_mov_b32 v[78:79], v[78:79], v[70:71] op_sel:[1,0] op_sel_hi:[1,0]
	s_mov_b64 exec, s[88:89]
	v_pk_mov_b32 v[80:81], v[80:81], v[82:83] op_sel:[1,0] op_sel_hi:[1,0]
	v_pk_mov_b32 v[82:83], v[82:83], v[70:71] op_sel:[1,0] op_sel_hi:[1,0]
	s_mov_b64 exec, s[90:91]
	v_pk_mov_b32 v[84:85], v[84:85], v[86:87] op_sel:[1,0] op_sel_hi:[1,0]
	v_pk_mov_b32 v[86:87], v[86:87], v[70:71] op_sel:[1,0] op_sel_hi:[1,0]
	s_lshl_b64 exec, s[78:79], s40
	s_add_i32 s40, s40, 1
	v_pk_mov_b32 v[4:5], v[32:33], v[32:33] op_sel:[1,0] op_sel_hi:[1,0]
	v_pk_mov_b32 v[6:7], v[30:31], v[30:31] op_sel:[1,0] op_sel_hi:[1,0]
	s_mov_b64 exec, -1
	v_max_u32_dpp v31, v72, v72 row_ror:1 row_mask:0xf bank_mask:0xf bound_ctrl:1
	v_max_u32_dpp v30, v76, v76 row_ror:1 row_mask:0xf bank_mask:0xf bound_ctrl:1
	v_max_u32_dpp v32, v80, v80 row_ror:1 row_mask:0xf bank_mask:0xf bound_ctrl:1
	v_max_u32_dpp v31, v31, v31 row_ror:2 row_mask:0xf bank_mask:0xf bound_ctrl:1
	v_max_u32_dpp v33, v84, v84 row_ror:1 row_mask:0xf bank_mask:0xf bound_ctrl:1
	v_max_u32_dpp v30, v30, v30 row_ror:2 row_mask:0xf bank_mask:0xf bound_ctrl:1
	v_max_u32_dpp v32, v32, v32 row_ror:2 row_mask:0xf bank_mask:0xf bound_ctrl:1
	v_max_u32_dpp v31, v31, v31 row_ror:4 row_mask:0xf bank_mask:0xf bound_ctrl:1
	v_max_u32_dpp v33, v33, v33 row_ror:2 row_mask:0xf bank_mask:0xf bound_ctrl:1
	v_max_u32_dpp v30, v30, v30 row_ror:4 row_mask:0xf bank_mask:0xf bound_ctrl:1
	v_max_u32_dpp v32, v32, v32 row_ror:4 row_mask:0xf bank_mask:0xf bound_ctrl:1
	v_max_u32_dpp v31, v31, v31 row_ror:8 row_mask:0xf bank_mask:0xf bound_ctrl:1
	v_max_u32_dpp v33, v33, v33 row_ror:4 row_mask:0xf bank_mask:0xf bound_ctrl:1
	v_max_u32_dpp v30, v30, v30 row_ror:8 row_mask:0xf bank_mask:0xf bound_ctrl:1
	v_max_u32_dpp v32, v32, v32 row_ror:8 row_mask:0xf bank_mask:0xf bound_ctrl:1
	v_max_u32_dpp v33, v33, v33 row_ror:8 row_mask:0xf bank_mask:0xf bound_ctrl:1
	v_cmp_eq_u32_e64 s[84:85], v72, v31
	v_cmp_eq_u32_e64 s[86:87], v76, v30
	v_cmp_eq_u32_e64 s[88:89], v80, v32
	v_cmp_eq_u32_e64 s[90:91], v84, v33
	s_mov_b64 exec, s[84:85]
	v_pk_mov_b32 v[72:73], v[72:73], v[74:75] op_sel:[1,0] op_sel_hi:[1,0]
	v_pk_mov_b32 v[74:75], v[74:75], v[70:71] op_sel:[1,0] op_sel_hi:[1,0]
	s_mov_b64 exec, s[86:87]
	v_pk_mov_b32 v[76:77], v[76:77], v[78:79] op_sel:[1,0] op_sel_hi:[1,0]
	v_pk_mov_b32 v[78:79], v[78:79], v[70:71] op_sel:[1,0] op_sel_hi:[1,0]
	s_mov_b64 exec, s[88:89]
	v_pk_mov_b32 v[80:81], v[80:81], v[82:83] op_sel:[1,0] op_sel_hi:[1,0]
	v_pk_mov_b32 v[82:83], v[82:83], v[70:71] op_sel:[1,0] op_sel_hi:[1,0]
	s_mov_b64 exec, s[90:91]
	v_pk_mov_b32 v[84:85], v[84:85], v[86:87] op_sel:[1,0] op_sel_hi:[1,0]
	v_pk_mov_b32 v[86:87], v[86:87], v[70:71] op_sel:[1,0] op_sel_hi:[1,0]
	s_lshl_b64 exec, s[78:79], s40
	s_add_i32 s40, s40, 1
	v_pk_mov_b32 v[4:5], v[32:33], v[32:33] op_sel:[1,0] op_sel_hi:[1,0]
	v_pk_mov_b32 v[6:7], v[30:31], v[30:31] op_sel:[1,0] op_sel_hi:[1,0]
	s_mov_b64 exec, -1
	v_max_u32_dpp v31, v72, v72 row_ror:1 row_mask:0xf bank_mask:0xf bound_ctrl:1
	v_max_u32_dpp v30, v76, v76 row_ror:1 row_mask:0xf bank_mask:0xf bound_ctrl:1
	v_max_u32_dpp v32, v80, v80 row_ror:1 row_mask:0xf bank_mask:0xf bound_ctrl:1
	v_max_u32_dpp v31, v31, v31 row_ror:2 row_mask:0xf bank_mask:0xf bound_ctrl:1
	v_max_u32_dpp v33, v84, v84 row_ror:1 row_mask:0xf bank_mask:0xf bound_ctrl:1
	v_max_u32_dpp v30, v30, v30 row_ror:2 row_mask:0xf bank_mask:0xf bound_ctrl:1
	v_max_u32_dpp v32, v32, v32 row_ror:2 row_mask:0xf bank_mask:0xf bound_ctrl:1
	v_max_u32_dpp v31, v31, v31 row_ror:4 row_mask:0xf bank_mask:0xf bound_ctrl:1
	v_max_u32_dpp v33, v33, v33 row_ror:2 row_mask:0xf bank_mask:0xf bound_ctrl:1
	v_max_u32_dpp v30, v30, v30 row_ror:4 row_mask:0xf bank_mask:0xf bound_ctrl:1
	v_max_u32_dpp v32, v32, v32 row_ror:4 row_mask:0xf bank_mask:0xf bound_ctrl:1
	v_max_u32_dpp v31, v31, v31 row_ror:8 row_mask:0xf bank_mask:0xf bound_ctrl:1
	v_max_u32_dpp v33, v33, v33 row_ror:4 row_mask:0xf bank_mask:0xf bound_ctrl:1
	v_max_u32_dpp v30, v30, v30 row_ror:8 row_mask:0xf bank_mask:0xf bound_ctrl:1
	v_max_u32_dpp v32, v32, v32 row_ror:8 row_mask:0xf bank_mask:0xf bound_ctrl:1
	v_max_u32_dpp v33, v33, v33 row_ror:8 row_mask:0xf bank_mask:0xf bound_ctrl:1
	v_cmp_eq_u32_e64 s[84:85], v72, v31
	v_cmp_eq_u32_e64 s[86:87], v76, v30
	v_cmp_eq_u32_e64 s[88:89], v80, v32
	v_cmp_eq_u32_e64 s[90:91], v84, v33
	s_mov_b64 exec, s[84:85]
	v_pk_mov_b32 v[72:73], v[72:73], v[74:75] op_sel:[1,0] op_sel_hi:[1,0]
	s_mov_b64 exec, s[86:87]
	v_pk_mov_b32 v[76:77], v[76:77], v[78:79] op_sel:[1,0] op_sel_hi:[1,0]
	s_mov_b64 exec, s[88:89]
	v_pk_mov_b32 v[80:81], v[80:81], v[82:83] op_sel:[1,0] op_sel_hi:[1,0]
	s_mov_b64 exec, s[90:91]
	v_pk_mov_b32 v[84:85], v[84:85], v[86:87] op_sel:[1,0] op_sel_hi:[1,0]
	s_lshl_b64 exec, s[78:79], s40
	s_add_i32 s40, s40, 1
	v_pk_mov_b32 v[4:5], v[32:33], v[32:33] op_sel:[1,0] op_sel_hi:[1,0]
	v_pk_mov_b32 v[6:7], v[30:31], v[30:31] op_sel:[1,0] op_sel_hi:[1,0]
	s_mov_b64 exec, -1
	v_max_u32_dpp v31, v72, v72 row_ror:1 row_mask:0xf bank_mask:0xf bound_ctrl:1
	v_max_u32_dpp v30, v76, v76 row_ror:1 row_mask:0xf bank_mask:0xf bound_ctrl:1
	v_max_u32_dpp v32, v80, v80 row_ror:1 row_mask:0xf bank_mask:0xf bound_ctrl:1
	v_max_u32_dpp v31, v31, v31 row_ror:2 row_mask:0xf bank_mask:0xf bound_ctrl:1
	v_max_u32_dpp v33, v84, v84 row_ror:1 row_mask:0xf bank_mask:0xf bound_ctrl:1
	v_max_u32_dpp v30, v30, v30 row_ror:2 row_mask:0xf bank_mask:0xf bound_ctrl:1
	v_max_u32_dpp v32, v32, v32 row_ror:2 row_mask:0xf bank_mask:0xf bound_ctrl:1
	v_max_u32_dpp v31, v31, v31 row_ror:4 row_mask:0xf bank_mask:0xf bound_ctrl:1
	v_max_u32_dpp v33, v33, v33 row_ror:2 row_mask:0xf bank_mask:0xf bound_ctrl:1
	v_max_u32_dpp v30, v30, v30 row_ror:4 row_mask:0xf bank_mask:0xf bound_ctrl:1
	v_max_u32_dpp v32, v32, v32 row_ror:4 row_mask:0xf bank_mask:0xf bound_ctrl:1
	v_max_u32_dpp v31, v31, v31 row_ror:8 row_mask:0xf bank_mask:0xf bound_ctrl:1
	v_max_u32_dpp v33, v33, v33 row_ror:4 row_mask:0xf bank_mask:0xf bound_ctrl:1
	v_max_u32_dpp v30, v30, v30 row_ror:8 row_mask:0xf bank_mask:0xf bound_ctrl:1
	v_max_u32_dpp v32, v32, v32 row_ror:8 row_mask:0xf bank_mask:0xf bound_ctrl:1
	v_max_u32_dpp v33, v33, v33 row_ror:8 row_mask:0xf bank_mask:0xf bound_ctrl:1
	v_cmp_eq_u32_e64 s[84:85], v72, v31
	v_cmp_eq_u32_e64 s[86:87], v76, v30
	v_cmp_eq_u32_e64 s[88:89], v80, v32
	v_cmp_eq_u32_e64 s[90:91], v84, v33
	s_mov_b64 exec, s[84:85]
	v_pk_mov_b32 v[72:73], v[72:73], v[74:75] op_sel:[1,0] op_sel_hi:[1,0]
	s_mov_b64 exec, s[86:87]
	v_pk_mov_b32 v[76:77], v[76:77], v[78:79] op_sel:[1,0] op_sel_hi:[1,0]
	s_mov_b64 exec, s[88:89]
	v_pk_mov_b32 v[80:81], v[80:81], v[82:83] op_sel:[1,0] op_sel_hi:[1,0]
	s_mov_b64 exec, s[90:91]
	v_pk_mov_b32 v[84:85], v[84:85], v[86:87] op_sel:[1,0] op_sel_hi:[1,0]
	s_lshl_b64 exec, s[78:79], s40
	s_add_i32 s40, s40, 1
	v_pk_mov_b32 v[4:5], v[32:33], v[32:33] op_sel:[1,0] op_sel_hi:[1,0]
	v_pk_mov_b32 v[6:7], v[30:31], v[30:31] op_sel:[1,0] op_sel_hi:[1,0]
	s_mov_b64 exec, -1
	v_max_u32_dpp v31, v72, v72 row_ror:1 row_mask:0xf bank_mask:0xf bound_ctrl:1
	v_max_u32_dpp v30, v76, v76 row_ror:1 row_mask:0xf bank_mask:0xf bound_ctrl:1
	v_max_u32_dpp v32, v80, v80 row_ror:1 row_mask:0xf bank_mask:0xf bound_ctrl:1
	v_max_u32_dpp v31, v31, v31 row_ror:2 row_mask:0xf bank_mask:0xf bound_ctrl:1
	v_max_u32_dpp v33, v84, v84 row_ror:1 row_mask:0xf bank_mask:0xf bound_ctrl:1
	v_max_u32_dpp v30, v30, v30 row_ror:2 row_mask:0xf bank_mask:0xf bound_ctrl:1
	v_max_u32_dpp v32, v32, v32 row_ror:2 row_mask:0xf bank_mask:0xf bound_ctrl:1
	v_max_u32_dpp v31, v31, v31 row_ror:4 row_mask:0xf bank_mask:0xf bound_ctrl:1
	v_max_u32_dpp v33, v33, v33 row_ror:2 row_mask:0xf bank_mask:0xf bound_ctrl:1
	v_max_u32_dpp v30, v30, v30 row_ror:4 row_mask:0xf bank_mask:0xf bound_ctrl:1
	v_max_u32_dpp v32, v32, v32 row_ror:4 row_mask:0xf bank_mask:0xf bound_ctrl:1
	v_max_u32_dpp v31, v31, v31 row_ror:8 row_mask:0xf bank_mask:0xf bound_ctrl:1
	v_max_u32_dpp v33, v33, v33 row_ror:4 row_mask:0xf bank_mask:0xf bound_ctrl:1
	v_max_u32_dpp v30, v30, v30 row_ror:8 row_mask:0xf bank_mask:0xf bound_ctrl:1
	v_max_u32_dpp v32, v32, v32 row_ror:8 row_mask:0xf bank_mask:0xf bound_ctrl:1
	v_max_u32_dpp v33, v33, v33 row_ror:8 row_mask:0xf bank_mask:0xf bound_ctrl:1
	s_lshl_b64 exec, s[78:79], s40
	v_pk_mov_b32 v[4:5], v[32:33], v[32:33] op_sel:[1,0] op_sel_hi:[1,0]
	v_pk_mov_b32 v[6:7], v[30:31], v[30:31] op_sel:[1,0] op_sel_hi:[1,0]
	s_mov_b64 exec, -1
	v_max_u32_dpp v15, v7, v7 row_ror:1 row_mask:0xf bank_mask:0xf bound_ctrl:1
	v_cmp_lt_i32_e32 vcc, -1, v7
	v_bitop3_b32 v11, v18, s60, v18 bitop3:0xc
	v_max_u32_dpp v15, v15, v15 row_ror:2 row_mask:0xf bank_mask:0xf bound_ctrl:1
	v_cndmask_b32_e64 v14, v217, -1, vcc
	v_bitop3_b32 v14, v14, v7, s59 bitop3:0x78
	v_max_u32_dpp v15, v15, v15 row_ror:4 row_mask:0xf bank_mask:0xf bound_ctrl:1
	v_not_b32_e32 v13, v7
	v_lshrrev_b32_e32 v13, 4, v13
	v_max_u32_dpp v15, v15, v15 row_ror:8 row_mask:0xf bank_mask:0xf bound_ctrl:1
	v_cmp_lt_i32_e32 vcc, -1, v15
	v_and_or_b32 v13, v13, 15, v195
	v_lshlrev_b32_e32 v13, 2, v13
	v_cndmask_b32_e64 v18, v217, -1, vcc
	v_bitop3_b32 v15, v18, v15, s59 bitop3:0x78
	v_sub_f32_e32 v14, v14, v15
	v_mul_f32_e32 v14, 0x3fb8aa3b, v14
	v_exp_f32_e32 v14, v14
	ds_bpermute_b32 v11, v13, v11
	v_bitop3_b32 v7, v7, v195, 15 bitop3:0xce
	v_bitop3_b32 v0, v0, s60, v0 bitop3:0xc
	v_add_f32_dpp v13, v14, v14 row_ror:1 row_mask:0xf bank_mask:0xf bound_ctrl:1
	v_lshlrev_b32_e32 v7, 2, v7
	ds_bpermute_b32 v0, v7, v0
	v_add_f32_dpp v13, v13, v13 row_ror:2 row_mask:0xf bank_mask:0xf bound_ctrl:1
	v_bitop3_b32 v10, v19, s60, v19 bitop3:0xc
	v_bitop3_b32 v9, v20, s60, v20 bitop3:0xc
	v_add_f32_dpp v13, v13, v13 row_ror:4 row_mask:0xf bank_mask:0xf bound_ctrl:1
	v_lshl_or_b32 v12, s33, 4, v171
	s_waitcnt lgkmcnt(0)
	v_lshl_add_u32 v0, v11, 7, v0
	v_add_f32_dpp v13, v13, v13 row_ror:8 row_mask:0xf bank_mask:0xf bound_ctrl:1
	v_div_scale_f32 v15, s[0:1], v13, v13, v14
	v_rcp_f32_e32 v18, v15
	v_bitop3_b32 v1, v1, s60, v1 bitop3:0xc
	v_bitop3_b32 v2, v2, s60, v2 bitop3:0xc
	v_bitop3_b32 v3, v3, s60, v3 bitop3:0xc
	v_fma_f32 v7, -v15, v18, 1.0
	v_fmac_f32_e32 v18, v7, v18
	v_div_scale_f32 v7, vcc, v14, v13, v14
	v_mul_f32_e32 v19, v7, v18
	v_fma_f32 v20, -v15, v19, v7
	v_fmac_f32_e32 v19, v20, v18
	v_fma_f32 v7, -v15, v19, v7
	v_div_fmas_f32 v7, v7, v18, v19
	v_div_fixup_f32 v7, v7, v13, v14
	v_or_b32_e32 v13, v12, v183
	v_lshl_add_u32 v11, v13, 1, s63
	v_cvt_f16_f32_e32 v7, v7
	v_max_u32_dpp v13, v6, v6 row_ror:1 row_mask:0xf bank_mask:0xf bound_ctrl:1
	v_cmp_lt_i32_e32 vcc, -1, v6
	ds_write_b16 v11, v0
	ds_write_b16 v11, v7 offset:32768
	v_max_u32_dpp v13, v13, v13 row_ror:2 row_mask:0xf bank_mask:0xf bound_ctrl:1
	v_cndmask_b32_e64 v7, v217, -1, vcc
	v_bitop3_b32 v7, v7, v6, s59 bitop3:0x78
	v_max_u32_dpp v13, v13, v13 row_ror:4 row_mask:0xf bank_mask:0xf bound_ctrl:1
	v_not_b32_e32 v0, v6
	v_lshrrev_b32_e32 v0, 4, v0
	v_max_u32_dpp v13, v13, v13 row_ror:8 row_mask:0xf bank_mask:0xf bound_ctrl:1
	v_cmp_lt_i32_e32 vcc, -1, v13
	v_and_or_b32 v0, v0, 15, v195
	v_lshlrev_b32_e32 v0, 2, v0
	v_cndmask_b32_e64 v14, v217, -1, vcc
	v_bitop3_b32 v13, v14, v13, s59 bitop3:0x78
	v_sub_f32_e32 v7, v7, v13
	v_mul_f32_e32 v7, 0x3fb8aa3b, v7
	v_exp_f32_e32 v7, v7
	ds_bpermute_b32 v0, v0, v10
	v_bitop3_b32 v6, v6, v195, 15 bitop3:0xce
	v_lshlrev_b32_e32 v6, 2, v6
	v_add_f32_dpp v10, v7, v7 row_ror:1 row_mask:0xf bank_mask:0xf bound_ctrl:1
	ds_bpermute_b32 v1, v6, v1
	v_bitop3_b32 v8, v21, s60, v21 bitop3:0xc
	v_add_f32_dpp v10, v10, v10 row_ror:2 row_mask:0xf bank_mask:0xf bound_ctrl:1
	s_waitcnt lgkmcnt(0)
	v_lshl_add_u32 v0, v0, 7, v1
	v_add_f32_dpp v10, v10, v10 row_ror:4 row_mask:0xf bank_mask:0xf bound_ctrl:1
	ds_write_b16 v11, v0 offset:256
	v_not_b32_e32 v1, v5
	v_add_f32_dpp v10, v10, v10 row_ror:8 row_mask:0xf bank_mask:0xf bound_ctrl:1
	v_div_scale_f32 v13, s[0:1], v10, v10, v7
	v_rcp_f32_e32 v14, v13
	v_lshrrev_b32_e32 v1, 4, v1
	v_and_or_b32 v1, v1, 15, v195
	v_lshlrev_b32_e32 v1, 2, v1
	v_fma_f32 v6, -v13, v14, 1.0
	v_fmac_f32_e32 v14, v6, v14
	v_div_scale_f32 v6, vcc, v7, v10, v7
	v_mul_f32_e32 v15, v6, v14
	v_fma_f32 v18, -v13, v15, v6
	v_fmac_f32_e32 v15, v18, v14
	v_fma_f32 v6, -v13, v15, v6
	v_div_fmas_f32 v6, v6, v14, v15
	v_div_fixup_f32 v6, v6, v10, v7
	v_max_u32_dpp v7, v5, v5 row_ror:1 row_mask:0xf bank_mask:0xf bound_ctrl:1
	v_cmp_lt_i32_e32 vcc, -1, v5
	v_cvt_f16_f32_e32 v0, v6
	v_max_u32_dpp v7, v7, v7 row_ror:2 row_mask:0xf bank_mask:0xf bound_ctrl:1
	v_cndmask_b32_e64 v6, v217, -1, vcc
	v_bitop3_b32 v6, v6, v5, s59 bitop3:0x78
	v_max_u32_dpp v7, v7, v7 row_ror:4 row_mask:0xf bank_mask:0xf bound_ctrl:1
	ds_bpermute_b32 v1, v1, v9
	v_bitop3_b32 v5, v5, v195, 15 bitop3:0xce
	v_max_u32_dpp v7, v7, v7 row_ror:8 row_mask:0xf bank_mask:0xf bound_ctrl:1
	v_cmp_lt_i32_e32 vcc, -1, v7
	v_lshlrev_b32_e32 v5, 2, v5
	ds_bpermute_b32 v2, v5, v2
	v_cndmask_b32_e64 v10, v217, -1, vcc
	v_bitop3_b32 v7, v10, v7, s59 bitop3:0x78
	v_sub_f32_e32 v6, v6, v7
	v_mul_f32_e32 v6, 0x3fb8aa3b, v6
	v_exp_f32_e32 v6, v6
	ds_write_b16 v11, v0 offset:33024
	s_waitcnt lgkmcnt(1)
	v_lshl_add_u32 v0, v1, 7, v2
	v_max_u32_dpp v2, v4, v4 row_ror:1 row_mask:0xf bank_mask:0xf bound_ctrl:1
	v_add_f32_dpp v7, v6, v6 row_ror:1 row_mask:0xf bank_mask:0xf bound_ctrl:1
	s_nop 0
	v_max_u32_dpp v2, v2, v2 row_ror:2 row_mask:0xf bank_mask:0xf bound_ctrl:1
	v_add_f32_dpp v7, v7, v7 row_ror:2 row_mask:0xf bank_mask:0xf bound_ctrl:1
	s_nop 0
	v_max_u32_dpp v2, v2, v2 row_ror:4 row_mask:0xf bank_mask:0xf bound_ctrl:1
	v_add_f32_dpp v7, v7, v7 row_ror:4 row_mask:0xf bank_mask:0xf bound_ctrl:1
	s_nop 0
	v_max_u32_dpp v2, v2, v2 row_ror:8 row_mask:0xf bank_mask:0xf bound_ctrl:1
	v_add_f32_dpp v7, v7, v7 row_ror:8 row_mask:0xf bank_mask:0xf bound_ctrl:1
	v_div_scale_f32 v9, s[0:1], v7, v7, v6
	v_rcp_f32_e32 v10, v9
	s_nop 0
	v_fma_f32 v5, -v9, v10, 1.0
	v_fmac_f32_e32 v10, v5, v10
	v_div_scale_f32 v5, vcc, v6, v7, v6
	v_mul_f32_e32 v13, v5, v10
	v_fma_f32 v14, -v9, v13, v5
	v_fmac_f32_e32 v13, v14, v10
	v_fma_f32 v5, -v9, v13, v5
	v_div_fmas_f32 v5, v5, v10, v13
	v_div_fixup_f32 v5, v5, v7, v6
	v_cvt_f16_f32_e32 v5, v5
	v_cmp_lt_i32_e32 vcc, -1, v4
	ds_write_b16 v11, v0 offset:512
	ds_write_b16 v11, v5 offset:33280
	v_cndmask_b32_e64 v1, v217, -1, vcc
	v_cmp_lt_i32_e32 vcc, -1, v2
	v_bitop3_b32 v1, v1, v4, s59 bitop3:0x78
	v_not_b32_e32 v0, v4
	v_cndmask_b32_e64 v5, v217, -1, vcc
	v_bitop3_b32 v2, v5, v2, s59 bitop3:0x78
	v_sub_f32_e32 v1, v1, v2
	v_mul_f32_e32 v1, 0x3fb8aa3b, v1
	v_exp_f32_e32 v1, v1
	v_bitop3_b32 v4, v4, v195, 15 bitop3:0xce
	v_lshlrev_b32_e32 v4, 2, v4
	v_lshrrev_b32_e32 v0, 4, v0
	v_add_f32_dpp v2, v1, v1 row_ror:1 row_mask:0xf bank_mask:0xf bound_ctrl:1
	ds_bpermute_b32 v3, v4, v3
	v_and_or_b32 v0, v0, 15, v195
	v_add_f32_dpp v2, v2, v2 row_ror:2 row_mask:0xf bank_mask:0xf bound_ctrl:1
	v_lshlrev_b32_e32 v0, 2, v0
	ds_bpermute_b32 v0, v0, v8
	v_add_f32_dpp v2, v2, v2 row_ror:4 row_mask:0xf bank_mask:0xf bound_ctrl:1
	s_waitcnt lgkmcnt(0)
	v_lshl_add_u32 v0, v0, 7, v3
	v_add_f32_dpp v2, v2, v2 row_ror:8 row_mask:0xf bank_mask:0xf bound_ctrl:1
	v_div_scale_f32 v5, s[0:1], v2, v2, v1
	v_rcp_f32_e32 v6, v5
	s_add_i32 s0, s33, 1
	s_cmp_lg_u32 s33, 7
	s_cselect_b32 s1, s0, 7
	v_fma_f32 v4, -v5, v6, 1.0
	v_fmac_f32_e32 v6, v4, v6
	v_div_scale_f32 v4, vcc, v1, v2, v1
	v_mul_f32_e32 v7, v4, v6
	v_fma_f32 v8, -v5, v7, v4
	v_fmac_f32_e32 v7, v8, v6
	v_fma_f32 v4, -v5, v7, v4
	v_div_fmas_f32 v4, v4, v6, v7
	v_div_fixup_f32 v1, v4, v2, v1
	v_add_u32_e32 v2, v12, v182
	v_cvt_f16_f32_e32 v1, v1
	v_lshl_or_b32 v2, v2, 1, v218
	s_lshl_b32 s40, s1, 16
	v_add_u32_e32 v2, s63, v2
	s_cmp_lt_u32 s1, 4
	ds_write_b16 v2, v0
	ds_write_b16 v2, v1 offset:32768
	v_lshl_add_u64 v[0:1], v[154:155], 0, s[40:41]
	s_cselect_b32 s33, s3, s56
	s_cselect_b32 s40, s2, s55
	v_mov_b32_e32 v2, s40
	v_mov_b32_e32 v3, s33
	s_lshl_b32 s1, s1, 9
	v_lshl_add_u64 v[2:3], v[16:17], 1, v[2:3]
	s_and_b32 s40, s1, 0x600
	v_lshl_add_u64 v[2:3], v[2:3], 0, s[40:41]
	v_lshl_add_u64 v[12:13], v[2:3], 0, v[148:149]
	s_cmp_eq_u32 s0, 8
	s_mov_b32 s33, s0
	s_cbranch_scc0 .LBB0_1346
	s_waitcnt lgkmcnt(0)
	s_barrier
	ds_read_b128 v[0:3], v185
	ds_read_b128 v[40:43], v185 offset:16
	s_ashr_i32 s49, s48, 31
	s_lshl_b64 s[0:1], s[48:49], 10
	v_lshl_add_u64 v[144:145], v[152:153], 0, s[0:1]
	s_waitcnt lgkmcnt(1)
	v_lshlrev_b32_e32 v4, 7, v0
	v_mad_u32_u16 v0, v0, s81, v150 op_sel:[1,0,0,0]
	v_and_or_b32 v64, v4, s68, v150
	v_mad_u32_u16 v4, v1, s81, v150
	global_load_dwordx4 v[60:63], v0, s[26:27]
	global_load_dwordx4 v[56:59], v4, s[26:27]
	v_mad_u32_u16 v0, v1, s81, v150 op_sel:[1,0,0,0]
	v_mad_u32_u16 v1, v2, s81, v150
	global_load_dwordx4 v[52:55], v0, s[26:27]
	global_load_dwordx4 v[48:51], v1, s[26:27]
	v_mad_u32_u16 v0, v2, s81, v150 op_sel:[1,0,0,0]
	v_mad_u32_u16 v1, v3, s81, v150
	global_load_dwordx4 v[44:47], v0, s[26:27]
	global_load_dwordx4 v[36:39], v1, s[26:27]
	v_mad_u32_u16 v0, v3, s81, v150 op_sel:[1,0,0,0]
	s_waitcnt lgkmcnt(0)
	v_mad_u32_u16 v1, v40, s81, v150
	global_load_dwordx4 v[32:35], v0, s[26:27]
	global_load_dwordx4 v[28:31], v1, s[26:27]
	v_mad_u32_u16 v0, v40, s81, v150 op_sel:[1,0,0,0]
	v_mad_u32_u16 v1, v41, s81, v150
	global_load_dwordx4 v[24:27], v0, s[26:27]
	global_load_dwordx4 v[20:23], v1, s[26:27]
	v_mad_u32_u16 v0, v41, s81, v150 op_sel:[1,0,0,0]
	v_mad_u32_u16 v1, v42, s81, v150
	global_load_dwordx4 v[16:19], v0, s[26:27]
	global_load_dwordx4 v[12:15], v1, s[26:27]
	v_mad_u32_u16 v0, v42, s81, v150 op_sel:[1,0,0,0]
	v_mad_u32_u16 v1, v43, s81, v150
	global_load_dwordx4 v[8:11], v0, s[26:27]
	global_load_dwordx4 v[4:7], v1, s[26:27]
	v_mad_u32_u16 v0, v43, s81, v150 op_sel:[1,0,0,0]
	global_load_dwordx4 v[0:3], v0, s[26:27]
	s_nop 0
	global_load_dwordx4 v[64:67], v64, s[26:27]
	s_nop 0
	global_load_dwordx4 v[40:43], v[144:145], off
	ds_read_b128 v[140:143], v185 offset:256
	ds_read_b128 v[136:139], v185 offset:272
	ds_read_b32 v147, v185
	ds_read_b32 v147, v185
	s_mov_b32 s76, 0
	s_branch .LBB0_1379

.LBB0_1379:
	s_lshr_b32 s52, s76, 4
	s_lshl_b32 s33, s52, 21
	s_add_u32 s50, s26, s33
	s_waitcnt lgkmcnt(3)
	v_mad_u32_u16 v68, v140, s81, v150
	v_mad_u32_u16 v69, v140, s81, v150 op_sel:[1,0,0,0]
	s_addc_u32 s51, s27, 0
	global_load_dwordx4 v[132:135], v68, s[50:51]
	global_load_dwordx4 v[128:131], v69, s[50:51]
	v_mad_u32_u16 v68, v141, s81, v150
	v_mad_u32_u16 v69, v141, s81, v150 op_sel:[1,0,0,0]
	global_load_dwordx4 v[124:127], v68, s[50:51]
	global_load_dwordx4 v[120:123], v69, s[50:51]
	v_mad_u32_u16 v68, v142, s81, v150
	v_mad_u32_u16 v69, v142, s81, v150 op_sel:[1,0,0,0]
	global_load_dwordx4 v[116:119], v68, s[50:51]
	global_load_dwordx4 v[112:115], v69, s[50:51]
	v_mad_u32_u16 v68, v143, s81, v150
	v_mad_u32_u16 v69, v143, s81, v150 op_sel:[1,0,0,0]
	global_load_dwordx4 v[108:111], v68, s[50:51]
	global_load_dwordx4 v[104:107], v69, s[50:51]
	s_waitcnt lgkmcnt(2)
	v_mad_u32_u16 v68, v136, s81, v150
	v_mad_u32_u16 v69, v136, s81, v150 op_sel:[1,0,0,0]
	global_load_dwordx4 v[100:103], v68, s[50:51]
	global_load_dwordx4 v[96:99], v69, s[50:51]
	v_mad_u32_u16 v68, v137, s81, v150
	v_mad_u32_u16 v69, v137, s81, v150 op_sel:[1,0,0,0]
	global_load_dwordx4 v[92:95], v68, s[50:51]
	global_load_dwordx4 v[88:91], v69, s[50:51]
	v_mad_u32_u16 v68, v138, s81, v150
	v_mad_u32_u16 v69, v138, s81, v150 op_sel:[1,0,0,0]
	s_add_i32 s33, s76, 2
	s_cmpk_gt_u32 s76, 0x7d
	global_load_dwordx4 v[84:87], v68, s[50:51]
	global_load_dwordx4 v[76:79], v69, s[50:51]
	v_mad_u32_u16 v68, v139, s81, v150
	v_mad_u32_u16 v69, v139, s81, v150 op_sel:[1,0,0,0]
	s_cselect_b64 s[48:49], -1, 0
	s_cmpk_lt_u32 s76, 0x7e
	s_cselect_b32 s77, s33, 0x7f
	global_load_dwordx4 v[72:75], v68, s[50:51]
	s_nop 0
	global_load_dwordx4 v[68:71], v69, s[50:51]
	s_and_b32 s50, s76, 14
	s_or_b32 s45, s50, 1
	s_lshl_b32 s40, s45, 10
	v_lshl_add_u64 v[80:81], v[144:145], 0, s[40:41]
	s_lshl_b32 s40, s52, 7
	v_lshl_add_u64 v[80:81], v[80:81], 0, s[40:41]
	global_load_dwordx4 v[80:83], v[80:81], off
	s_and_b32 s40, s77, 15
	v_lshl_add_u32 v136, s40, 8, v185
	ds_read_b128 v[140:143], v136
	ds_read_b128 v[136:139], v136 offset:16
	v_mov_b32_e32 v146, 0
	s_waitcnt vmcnt(17)
	v_dot4c_i32_i8_e32 v146, v40, v64
	v_mov_b32_e32 v64, 0
	v_dot4c_i32_i8_e32 v64, v40, v60
	v_mov_b32_e32 v60, 0
	v_dot4c_i32_i8_e32 v60, v40, v56
	v_mov_b32_e32 v56, 0
	v_dot4c_i32_i8_e32 v56, v40, v52
	v_mov_b32_e32 v52, 0
	v_dot4c_i32_i8_e32 v52, v40, v48
	v_mov_b32_e32 v48, 0
	v_dot4c_i32_i8_e32 v48, v40, v44
	v_mov_b32_e32 v44, 0
	v_dot4c_i32_i8_e32 v44, v40, v36
	v_mov_b32_e32 v36, 0
	v_dot4c_i32_i8_e32 v36, v40, v32
	v_mov_b32_e32 v32, 0
	v_dot4c_i32_i8_e32 v32, v40, v28
	v_mov_b32_e32 v28, 0
	v_dot4c_i32_i8_e32 v28, v40, v24
	v_mov_b32_e32 v24, 0
	v_dot4c_i32_i8_e32 v24, v40, v20
	v_mov_b32_e32 v20, 0
	v_dot4c_i32_i8_e32 v20, v40, v16
	v_mov_b32_e32 v16, 0
	v_dot4c_i32_i8_e32 v16, v40, v12
	v_mov_b32_e32 v12, 0
	v_dot4c_i32_i8_e32 v64, v41, v61
	v_dot4c_i32_i8_e32 v12, v40, v8
	v_mov_b32_e32 v8, 0
	v_dot4c_i32_i8_e32 v146, v41, v65
	v_dot4c_i32_i8_e32 v64, v42, v62
	v_dot4c_i32_i8_e32 v32, v41, v29
	v_dot4c_i32_i8_e32 v28, v41, v25
	v_dot4c_i32_i8_e32 v8, v40, v4
	v_mov_b32_e32 v4, 0
	v_dot4c_i32_i8_e32 v146, v42, v66
	v_dot4c_i32_i8_e32 v64, v43, v63
	v_dot4c_i32_i8_e32 v60, v41, v57
	v_dot4c_i32_i8_e32 v32, v42, v30
	v_dot4c_i32_i8_e32 v28, v42, v26
	v_dot4c_i32_i8_e32 v24, v41, v21
	v_dot4c_i32_i8_e32 v16, v41, v13
	v_dot4c_i32_i8_e32 v12, v41, v9
	v_dot4c_i32_i8_e32 v4, v40, v0
	v_dot4c_i32_i8_e32 v146, v43, v67
	v_dot4c_i32_i8_e32 v60, v42, v58
	v_dot4c_i32_i8_e32 v56, v41, v53
	v_dot4c_i32_i8_e32 v32, v43, v31
	v_dot4c_i32_i8_e32 v28, v43, v27
	v_dot4c_i32_i8_e32 v24, v42, v22
	v_dot4c_i32_i8_e32 v20, v41, v17
	v_dot4c_i32_i8_e32 v16, v42, v14
	v_dot4c_i32_i8_e32 v12, v42, v10
	v_dot4c_i32_i8_e32 v4, v41, v1
	v_add_u32_dpp v1, v64, v64 quad_perm:[1,0,3,2] row_mask:0xf bank_mask:0xf bound_ctrl:1
	v_dot4c_i32_i8_e32 v60, v43, v59
	v_dot4c_i32_i8_e32 v56, v42, v54
	v_dot4c_i32_i8_e32 v52, v41, v49
	v_dot4c_i32_i8_e32 v24, v43, v23
	v_dot4c_i32_i8_e32 v20, v42, v18
	v_dot4c_i32_i8_e32 v16, v43, v15
	v_dot4c_i32_i8_e32 v12, v43, v11
	v_add_u32_dpp v0, v146, v146 quad_perm:[1,0,3,2] row_mask:0xf bank_mask:0xf bound_ctrl:1
	v_add_u32_dpp v10, v32, v32 quad_perm:[1,0,3,2] row_mask:0xf bank_mask:0xf bound_ctrl:1
	v_add_u32_dpp v11, v28, v28 quad_perm:[1,0,3,2] row_mask:0xf bank_mask:0xf bound_ctrl:1
	v_add_u32_dpp v1, v1, v1 quad_perm:[2,3,0,1] row_mask:0xf bank_mask:0xf bound_ctrl:1
	v_dot4c_i32_i8_e32 v56, v43, v55
	v_dot4c_i32_i8_e32 v52, v42, v50
	v_dot4c_i32_i8_e32 v48, v41, v45
	v_dot4c_i32_i8_e32 v20, v43, v19
	v_dot4c_i32_i8_e32 v4, v42, v2
	v_add_u32_dpp v2, v60, v60 quad_perm:[1,0,3,2] row_mask:0xf bank_mask:0xf bound_ctrl:1
	v_add_u32_dpp v13, v24, v24 quad_perm:[1,0,3,2] row_mask:0xf bank_mask:0xf bound_ctrl:1
	v_add_u32_dpp v15, v16, v16 quad_perm:[1,0,3,2] row_mask:0xf bank_mask:0xf bound_ctrl:1
	v_add_u32_dpp v0, v0, v0 quad_perm:[2,3,0,1] row_mask:0xf bank_mask:0xf bound_ctrl:1
	v_add_u32_dpp v10, v10, v10 quad_perm:[2,3,0,1] row_mask:0xf bank_mask:0xf bound_ctrl:1
	v_add_u32_dpp v11, v11, v11 quad_perm:[2,3,0,1] row_mask:0xf bank_mask:0xf bound_ctrl:1
	v_mov_b32_dpp v16, v1 row_half_mirror row_mask:0xf bank_mask:0xf bound_ctrl:1
	v_dot4c_i32_i8_e32 v52, v43, v51
	v_dot4c_i32_i8_e32 v48, v42, v46
	v_dot4c_i32_i8_e32 v44, v41, v37
	v_dot4c_i32_i8_e32 v8, v41, v5
	v_dot4c_i32_i8_e32 v4, v43, v3
	v_add_u32_dpp v3, v56, v56 quad_perm:[1,0,3,2] row_mask:0xf bank_mask:0xf bound_ctrl:1
	v_add_u32_dpp v14, v20, v20 quad_perm:[1,0,3,2] row_mask:0xf bank_mask:0xf bound_ctrl:1
	v_add_u32_dpp v2, v2, v2 quad_perm:[2,3,0,1] row_mask:0xf bank_mask:0xf bound_ctrl:1
	v_add_u32_dpp v13, v13, v13 quad_perm:[2,3,0,1] row_mask:0xf bank_mask:0xf bound_ctrl:1
	v_add_u32_dpp v0, v0, v0 row_half_mirror row_mask:0xf bank_mask:0xf bound_ctrl:1
	v_add_u32_dpp v10, v10, v10 row_half_mirror row_mask:0xf bank_mask:0xf bound_ctrl:1
	v_add_u32_dpp v11, v11, v11 row_half_mirror row_mask:0xf bank_mask:0xf bound_ctrl:1
	v_add_u32_e32 v1, v16, v1
	v_dot4c_i32_i8_e32 v48, v43, v47
	v_dot4c_i32_i8_e32 v44, v42, v38
	v_dot4c_i32_i8_e32 v36, v41, v33
	v_dot4c_i32_i8_e32 v8, v42, v6
	v_add_u32_dpp v5, v52, v52 quad_perm:[1,0,3,2] row_mask:0xf bank_mask:0xf bound_ctrl:1
	v_add_u32_dpp v3, v3, v3 quad_perm:[2,3,0,1] row_mask:0xf bank_mask:0xf bound_ctrl:1
	v_add_u32_dpp v14, v14, v14 quad_perm:[2,3,0,1] row_mask:0xf bank_mask:0xf bound_ctrl:1
	v_add_u32_dpp v2, v2, v2 row_half_mirror row_mask:0xf bank_mask:0xf bound_ctrl:1
	v_add_u32_dpp v13, v13, v13 row_half_mirror row_mask:0xf bank_mask:0xf bound_ctrl:1
	v_cndmask_b32_e64 v0, v0, v1, s[12:13]
	v_cndmask_b32_e64 v1, v10, v11, s[12:13]
	v_dot4c_i32_i8_e32 v44, v43, v39
	v_dot4c_i32_i8_e32 v36, v42, v34
	v_dot4c_i32_i8_e32 v8, v43, v7
	v_add_u32_dpp v6, v48, v48 quad_perm:[1,0,3,2] row_mask:0xf bank_mask:0xf bound_ctrl:1
	v_add_u32_dpp v12, v12, v12 quad_perm:[1,0,3,2] row_mask:0xf bank_mask:0xf bound_ctrl:1
	v_add_u32_dpp v5, v5, v5 quad_perm:[2,3,0,1] row_mask:0xf bank_mask:0xf bound_ctrl:1
	v_add_u32_dpp v15, v15, v15 quad_perm:[2,3,0,1] row_mask:0xf bank_mask:0xf bound_ctrl:1
	v_add_u32_dpp v3, v3, v3 row_half_mirror row_mask:0xf bank_mask:0xf bound_ctrl:1
	v_add_u32_dpp v14, v14, v14 row_half_mirror row_mask:0xf bank_mask:0xf bound_ctrl:1
	v_cndmask_b32_e64 v0, v0, v2, s[14:15]
	v_cndmask_b32_e64 v1, v1, v13, s[14:15]
	v_dot4c_i32_i8_e32 v36, v43, v35
	v_add_u32_dpp v7, v44, v44 quad_perm:[1,0,3,2] row_mask:0xf bank_mask:0xf bound_ctrl:1
	v_add_u32_dpp v8, v8, v8 quad_perm:[1,0,3,2] row_mask:0xf bank_mask:0xf bound_ctrl:1
	v_add_u32_dpp v6, v6, v6 quad_perm:[2,3,0,1] row_mask:0xf bank_mask:0xf bound_ctrl:1
	v_add_u32_dpp v12, v12, v12 quad_perm:[2,3,0,1] row_mask:0xf bank_mask:0xf bound_ctrl:1
	v_add_u32_dpp v5, v5, v5 row_half_mirror row_mask:0xf bank_mask:0xf bound_ctrl:1
	v_add_u32_dpp v15, v15, v15 row_half_mirror row_mask:0xf bank_mask:0xf bound_ctrl:1
	v_cndmask_b32_e64 v0, v0, v3, s[16:17]
	v_cndmask_b32_e64 v1, v1, v14, s[16:17]
	v_add_u32_dpp v9, v36, v36 quad_perm:[1,0,3,2] row_mask:0xf bank_mask:0xf bound_ctrl:1
	v_add_u32_dpp v4, v4, v4 quad_perm:[1,0,3,2] row_mask:0xf bank_mask:0xf bound_ctrl:1
	v_add_u32_dpp v7, v7, v7 quad_perm:[2,3,0,1] row_mask:0xf bank_mask:0xf bound_ctrl:1
	v_add_u32_dpp v8, v8, v8 quad_perm:[2,3,0,1] row_mask:0xf bank_mask:0xf bound_ctrl:1
	v_add_u32_dpp v6, v6, v6 row_half_mirror row_mask:0xf bank_mask:0xf bound_ctrl:1
	v_add_u32_dpp v12, v12, v12 row_half_mirror row_mask:0xf bank_mask:0xf bound_ctrl:1
	v_cndmask_b32_e64 v0, v0, v5, s[18:19]
	v_cndmask_b32_e64 v1, v1, v15, s[18:19]
	s_lshl_b32 s78, s50, 9
	v_add_u32_dpp v9, v9, v9 quad_perm:[2,3,0,1] row_mask:0xf bank_mask:0xf bound_ctrl:1
	v_add_u32_dpp v4, v4, v4 quad_perm:[2,3,0,1] row_mask:0xf bank_mask:0xf bound_ctrl:1
	v_add_u32_dpp v7, v7, v7 row_half_mirror row_mask:0xf bank_mask:0xf bound_ctrl:1
	v_add_u32_dpp v8, v8, v8 row_half_mirror row_mask:0xf bank_mask:0xf bound_ctrl:1
	v_cndmask_b32_e64 v0, v0, v6, s[20:21]
	v_cndmask_b32_e64 v1, v1, v12, s[20:21]
	s_cmp_gt_u32 s76, 15
	v_add_u32_dpp v9, v9, v9 row_half_mirror row_mask:0xf bank_mask:0xf bound_ctrl:1
	v_add_u32_dpp v4, v4, v4 row_half_mirror row_mask:0xf bank_mask:0xf bound_ctrl:1
	v_cndmask_b32_e64 v0, v0, v7, s[22:23]
	v_cndmask_b32_e64 v1, v1, v8, s[22:23]
	s_cselect_b64 s[50:51], -1, 0
	v_cndmask_b32_e64 v0, v0, v9, s[24:25]
	v_cndmask_b32_e64 v1, v1, v4, s[24:25]
	s_mov_b64 s[52:53], -1
	s_and_b64 vcc, exec, s[50:51]
	v_add_u32_e32 v2, s78, v186
	s_cbranch_vccz .LBB0_1381
	ds_add_u32 v2, v0
	ds_add_u32 v2, v1 offset:32
	s_mov_b64 s[52:53], 0
.LBB0_1381:
	s_andn2_b64 vcc, exec, s[52:53]
	s_cbranch_vccnz .LBB0_1383
	ds_write_b32 v2, v0
	ds_write_b32 v2, v1 offset:32
.LBB0_1383:
	s_lshr_b32 s77, s77, 4
	s_lshl_b32 s52, s77, 21
	s_add_u32 s52, s26, s52
	s_addc_u32 s53, s27, 0
	s_min_u32 s76, s76, 0x7c
	s_waitcnt lgkmcnt(3)
	v_mad_u32_u16 v0, v140, s81, v150
	v_mad_u32_u16 v1, v140, s81, v150 op_sel:[1,0,0,0]
	global_load_dwordx4 v[64:67], v0, s[52:53]
	global_load_dwordx4 v[60:63], v1, s[52:53]
	v_mad_u32_u16 v0, v141, s81, v150
	v_mad_u32_u16 v1, v141, s81, v150 op_sel:[1,0,0,0]
	global_load_dwordx4 v[56:59], v0, s[52:53]
	global_load_dwordx4 v[52:55], v1, s[52:53]
	v_mad_u32_u16 v0, v142, s81, v150
	v_mad_u32_u16 v1, v142, s81, v150 op_sel:[1,0,0,0]
	global_load_dwordx4 v[48:51], v0, s[52:53]
	global_load_dwordx4 v[44:47], v1, s[52:53]
	v_mad_u32_u16 v0, v143, s81, v150
	v_mad_u32_u16 v1, v143, s81, v150 op_sel:[1,0,0,0]
	global_load_dwordx4 v[36:39], v0, s[52:53]
	global_load_dwordx4 v[32:35], v1, s[52:53]
	s_waitcnt lgkmcnt(2)
	v_mad_u32_u16 v0, v136, s81, v150
	v_mad_u32_u16 v1, v136, s81, v150 op_sel:[1,0,0,0]
	global_load_dwordx4 v[28:31], v0, s[52:53]
	global_load_dwordx4 v[24:27], v1, s[52:53]
	v_mad_u32_u16 v0, v137, s81, v150
	v_mad_u32_u16 v1, v137, s81, v150 op_sel:[1,0,0,0]
	global_load_dwordx4 v[20:23], v0, s[52:53]
	global_load_dwordx4 v[16:19], v1, s[52:53]
	v_mad_u32_u16 v0, v138, s81, v150
	v_mad_u32_u16 v1, v138, s81, v150 op_sel:[1,0,0,0]
	s_lshl_b32 s40, s40, 10
	global_load_dwordx4 v[12:15], v0, s[52:53]
	global_load_dwordx4 v[8:11], v1, s[52:53]
	v_mad_u32_u16 v0, v139, s81, v150
	v_mad_u32_u16 v1, v139, s81, v150 op_sel:[1,0,0,0]
	v_lshl_add_u64 v[40:41], v[144:145], 0, s[40:41]
	s_lshl_b32 s40, s77, 7
	v_lshl_add_u64 v[40:41], v[40:41], 0, s[40:41]
	global_load_dwordx4 v[4:7], v0, s[52:53]
	s_nop 0
	global_load_dwordx4 v[0:3], v1, s[52:53]
	s_lshl_b32 s40, s76, 7
	global_load_dwordx4 v[40:43], v[40:41], off
	s_addk_i32 s40, 0x180
	s_and_b32 s40, s40, 0x780
	v_lshl_add_u32 v136, s40, 1, v185
	ds_read_b128 v[140:143], v136
	ds_read_b128 v[136:139], v136 offset:16
	v_mov_b32_e32 v146, 0
	s_waitcnt vmcnt(17)
	v_dot4c_i32_i8_e32 v146, v80, v132
	v_mov_b32_e32 v132, 0
	v_dot4c_i32_i8_e32 v132, v80, v128
	v_mov_b32_e32 v128, 0
	v_dot4c_i32_i8_e32 v128, v80, v124
	v_mov_b32_e32 v124, 0
	v_dot4c_i32_i8_e32 v124, v80, v120
	v_mov_b32_e32 v120, 0
	v_dot4c_i32_i8_e32 v120, v80, v116
	v_mov_b32_e32 v116, 0
	v_dot4c_i32_i8_e32 v116, v80, v112
	v_mov_b32_e32 v112, 0
	v_dot4c_i32_i8_e32 v112, v80, v108
	v_mov_b32_e32 v108, 0
	v_dot4c_i32_i8_e32 v108, v80, v104
	v_mov_b32_e32 v104, 0
	v_dot4c_i32_i8_e32 v104, v80, v100
	v_mov_b32_e32 v100, 0
	v_dot4c_i32_i8_e32 v100, v80, v96
	v_mov_b32_e32 v96, 0
	v_dot4c_i32_i8_e32 v96, v80, v92
	v_mov_b32_e32 v92, 0
	v_dot4c_i32_i8_e32 v92, v80, v88
	v_mov_b32_e32 v88, 0
	v_dot4c_i32_i8_e32 v88, v80, v84
	v_mov_b32_e32 v84, 0
	v_dot4c_i32_i8_e32 v132, v81, v129
	v_dot4c_i32_i8_e32 v84, v80, v76
	v_mov_b32_e32 v76, 0
	v_dot4c_i32_i8_e32 v146, v81, v133
	v_dot4c_i32_i8_e32 v132, v82, v130
	v_dot4c_i32_i8_e32 v104, v81, v101
	v_dot4c_i32_i8_e32 v100, v81, v97
	v_dot4c_i32_i8_e32 v76, v80, v72
	v_mov_b32_e32 v72, 0
	v_dot4c_i32_i8_e32 v146, v82, v134
	v_dot4c_i32_i8_e32 v132, v83, v131
	v_dot4c_i32_i8_e32 v128, v81, v125
	v_dot4c_i32_i8_e32 v104, v82, v102
	v_dot4c_i32_i8_e32 v100, v82, v98
	v_dot4c_i32_i8_e32 v96, v81, v93
	v_dot4c_i32_i8_e32 v84, v81, v77
	v_dot4c_i32_i8_e32 v72, v80, v68
	v_dot4c_i32_i8_e32 v146, v83, v135
	v_dot4c_i32_i8_e32 v128, v82, v126
	v_dot4c_i32_i8_e32 v124, v81, v121
	v_dot4c_i32_i8_e32 v120, v81, v117
	v_dot4c_i32_i8_e32 v116, v81, v113
	v_dot4c_i32_i8_e32 v112, v81, v109
	v_dot4c_i32_i8_e32 v108, v81, v105
	v_dot4c_i32_i8_e32 v104, v83, v103
	v_dot4c_i32_i8_e32 v100, v83, v99
	v_dot4c_i32_i8_e32 v96, v82, v94
	v_dot4c_i32_i8_e32 v92, v81, v89
	v_dot4c_i32_i8_e32 v88, v81, v85
	v_dot4c_i32_i8_e32 v84, v82, v78
	v_dot4c_i32_i8_e32 v76, v81, v73
	v_dot4c_i32_i8_e32 v72, v81, v69
	v_add_u32_dpp v69, v132, v132 quad_perm:[1,0,3,2] row_mask:0xf bank_mask:0xf bound_ctrl:1
	v_dot4c_i32_i8_e32 v128, v83, v127
	v_dot4c_i32_i8_e32 v124, v82, v122
	v_dot4c_i32_i8_e32 v120, v82, v118
	v_dot4c_i32_i8_e32 v116, v82, v114
	v_dot4c_i32_i8_e32 v112, v82, v110
	v_dot4c_i32_i8_e32 v108, v82, v106
	v_dot4c_i32_i8_e32 v96, v83, v95
	v_dot4c_i32_i8_e32 v92, v82, v90
	v_dot4c_i32_i8_e32 v88, v82, v86
	v_dot4c_i32_i8_e32 v84, v83, v79
	v_dot4c_i32_i8_e32 v76, v82, v74
	v_dot4c_i32_i8_e32 v72, v82, v70
	v_add_u32_dpp v68, v146, v146 quad_perm:[1,0,3,2] row_mask:0xf bank_mask:0xf bound_ctrl:1
	v_add_u32_dpp v78, v104, v104 quad_perm:[1,0,3,2] row_mask:0xf bank_mask:0xf bound_ctrl:1
	v_add_u32_dpp v79, v100, v100 quad_perm:[1,0,3,2] row_mask:0xf bank_mask:0xf bound_ctrl:1
	v_add_u32_dpp v69, v69, v69 quad_perm:[2,3,0,1] row_mask:0xf bank_mask:0xf bound_ctrl:1
	v_dot4c_i32_i8_e32 v124, v83, v123
	v_dot4c_i32_i8_e32 v120, v83, v119
	v_dot4c_i32_i8_e32 v116, v83, v115
	v_dot4c_i32_i8_e32 v112, v83, v111
	v_dot4c_i32_i8_e32 v108, v83, v107
	v_dot4c_i32_i8_e32 v92, v83, v91
	v_dot4c_i32_i8_e32 v88, v83, v87
	v_dot4c_i32_i8_e32 v76, v83, v75
	v_dot4c_i32_i8_e32 v72, v83, v71
	v_add_u32_dpp v70, v128, v128 quad_perm:[1,0,3,2] row_mask:0xf bank_mask:0xf bound_ctrl:1
	v_add_u32_dpp v80, v96, v96 quad_perm:[1,0,3,2] row_mask:0xf bank_mask:0xf bound_ctrl:1
	v_add_u32_dpp v83, v84, v84 quad_perm:[1,0,3,2] row_mask:0xf bank_mask:0xf bound_ctrl:1
	v_add_u32_dpp v68, v68, v68 quad_perm:[2,3,0,1] row_mask:0xf bank_mask:0xf bound_ctrl:1
	v_add_u32_dpp v78, v78, v78 quad_perm:[2,3,0,1] row_mask:0xf bank_mask:0xf bound_ctrl:1
	v_add_u32_dpp v79, v79, v79 quad_perm:[2,3,0,1] row_mask:0xf bank_mask:0xf bound_ctrl:1
	v_mov_b32_dpp v84, v69 row_half_mirror row_mask:0xf bank_mask:0xf bound_ctrl:1
	v_add_u32_dpp v71, v124, v124 quad_perm:[1,0,3,2] row_mask:0xf bank_mask:0xf bound_ctrl:1
	v_add_u32_dpp v81, v92, v92 quad_perm:[1,0,3,2] row_mask:0xf bank_mask:0xf bound_ctrl:1
	v_add_u32_dpp v70, v70, v70 quad_perm:[2,3,0,1] row_mask:0xf bank_mask:0xf bound_ctrl:1
	v_add_u32_dpp v80, v80, v80 quad_perm:[2,3,0,1] row_mask:0xf bank_mask:0xf bound_ctrl:1
	v_add_u32_dpp v68, v68, v68 row_half_mirror row_mask:0xf bank_mask:0xf bound_ctrl:1
	v_add_u32_dpp v78, v78, v78 row_half_mirror row_mask:0xf bank_mask:0xf bound_ctrl:1
	v_add_u32_dpp v79, v79, v79 row_half_mirror row_mask:0xf bank_mask:0xf bound_ctrl:1
	v_add_u32_e32 v69, v84, v69
	v_add_u32_dpp v73, v120, v120 quad_perm:[1,0,3,2] row_mask:0xf bank_mask:0xf bound_ctrl:1
	v_add_u32_dpp v82, v88, v88 quad_perm:[1,0,3,2] row_mask:0xf bank_mask:0xf bound_ctrl:1
	v_add_u32_dpp v71, v71, v71 quad_perm:[2,3,0,1] row_mask:0xf bank_mask:0xf bound_ctrl:1
	v_add_u32_dpp v81, v81, v81 quad_perm:[2,3,0,1] row_mask:0xf bank_mask:0xf bound_ctrl:1
	v_add_u32_dpp v70, v70, v70 row_half_mirror row_mask:0xf bank_mask:0xf bound_ctrl:1
	v_add_u32_dpp v80, v80, v80 row_half_mirror row_mask:0xf bank_mask:0xf bound_ctrl:1
	v_cndmask_b32_e64 v68, v68, v69, s[12:13]
	v_cndmask_b32_e64 v69, v78, v79, s[12:13]
	v_add_u32_dpp v74, v116, v116 quad_perm:[1,0,3,2] row_mask:0xf bank_mask:0xf bound_ctrl:1
	v_add_u32_dpp v73, v73, v73 quad_perm:[2,3,0,1] row_mask:0xf bank_mask:0xf bound_ctrl:1
	v_add_u32_dpp v82, v82, v82 quad_perm:[2,3,0,1] row_mask:0xf bank_mask:0xf bound_ctrl:1
	v_add_u32_dpp v71, v71, v71 row_half_mirror row_mask:0xf bank_mask:0xf bound_ctrl:1
	v_add_u32_dpp v81, v81, v81 row_half_mirror row_mask:0xf bank_mask:0xf bound_ctrl:1
	v_cndmask_b32_e64 v68, v68, v70, s[14:15]
	v_cndmask_b32_e64 v69, v69, v80, s[14:15]
	v_add_u32_dpp v75, v112, v112 quad_perm:[1,0,3,2] row_mask:0xf bank_mask:0xf bound_ctrl:1
	v_add_u32_dpp v76, v76, v76 quad_perm:[1,0,3,2] row_mask:0xf bank_mask:0xf bound_ctrl:1
	v_add_u32_dpp v74, v74, v74 quad_perm:[2,3,0,1] row_mask:0xf bank_mask:0xf bound_ctrl:1
	v_add_u32_dpp v83, v83, v83 quad_perm:[2,3,0,1] row_mask:0xf bank_mask:0xf bound_ctrl:1
	v_add_u32_dpp v73, v73, v73 row_half_mirror row_mask:0xf bank_mask:0xf bound_ctrl:1
	v_add_u32_dpp v82, v82, v82 row_half_mirror row_mask:0xf bank_mask:0xf bound_ctrl:1
	v_cndmask_b32_e64 v68, v68, v71, s[16:17]
	v_cndmask_b32_e64 v69, v69, v81, s[16:17]
	v_add_u32_dpp v77, v108, v108 quad_perm:[1,0,3,2] row_mask:0xf bank_mask:0xf bound_ctrl:1
	v_add_u32_dpp v72, v72, v72 quad_perm:[1,0,3,2] row_mask:0xf bank_mask:0xf bound_ctrl:1
	v_add_u32_dpp v75, v75, v75 quad_perm:[2,3,0,1] row_mask:0xf bank_mask:0xf bound_ctrl:1
	v_add_u32_dpp v76, v76, v76 quad_perm:[2,3,0,1] row_mask:0xf bank_mask:0xf bound_ctrl:1
	v_add_u32_dpp v74, v74, v74 row_half_mirror row_mask:0xf bank_mask:0xf bound_ctrl:1
	v_add_u32_dpp v83, v83, v83 row_half_mirror row_mask:0xf bank_mask:0xf bound_ctrl:1
	v_cndmask_b32_e64 v68, v68, v73, s[18:19]
	v_cndmask_b32_e64 v69, v69, v82, s[18:19]
	v_add_u32_dpp v77, v77, v77 quad_perm:[2,3,0,1] row_mask:0xf bank_mask:0xf bound_ctrl:1
	v_add_u32_dpp v72, v72, v72 quad_perm:[2,3,0,1] row_mask:0xf bank_mask:0xf bound_ctrl:1
	v_add_u32_dpp v75, v75, v75 row_half_mirror row_mask:0xf bank_mask:0xf bound_ctrl:1
	v_add_u32_dpp v76, v76, v76 row_half_mirror row_mask:0xf bank_mask:0xf bound_ctrl:1
	v_cndmask_b32_e64 v68, v68, v74, s[20:21]
	v_cndmask_b32_e64 v69, v69, v83, s[20:21]
	v_add_u32_dpp v77, v77, v77 row_half_mirror row_mask:0xf bank_mask:0xf bound_ctrl:1
	v_add_u32_dpp v72, v72, v72 row_half_mirror row_mask:0xf bank_mask:0xf bound_ctrl:1
	v_cndmask_b32_e64 v68, v68, v75, s[22:23]
	v_cndmask_b32_e64 v69, v69, v76, s[22:23]
	s_lshl_b32 s40, s45, 9
	v_cndmask_b32_e64 v68, v68, v77, s[24:25]
	v_cndmask_b32_e64 v69, v69, v72, s[24:25]
	s_mov_b64 s[52:53], -1
	s_and_b64 vcc, exec, s[50:51]
	v_add_u32_e32 v70, s40, v186
	s_cbranch_vccz .LBB0_1385
	ds_add_u32 v70, v68
	ds_add_u32 v70, v69 offset:32
	s_mov_b64 s[52:53], 0
.LBB0_1385:
	s_andn2_b64 vcc, exec, s[52:53]
	s_cbranch_vccnz .LBB0_1378
	ds_write_b32 v70, v68
	ds_write_b32 v70, v69 offset:32
	s_branch .LBB0_1378
